# context chain operands shared through LDS (96 KiB per workgroup instead of 320 KiB of per-wave fragment loads) on top of the 192x256 ffn1
# speedup vs baseline: 1.0128x; 1.0128x over previous
.Lsp3_entry:
	s_add_u32 s35, s63, 0x80
	v_and_b32_e32 v16, 63, v206
	v_lshrrev_b32_e32 v17, 6, v206
	v_and_b32_e32 v0, 15, v16
	v_readfirstlane_b32 s40, v17
	v_lshrrev_b32_e32 v1, 4, v16
	s_sub_u32 s38, s35, 0x80
	s_and_b32 s42, s40, 3
	s_lshr_b32 s43, s40, 2
	s_lshl_b32 s43, s43, 2
	s_lshr_b32 s100, s38, 4
	s_lshl_b32 s101, s100, 1
	s_bfe_u32 s41, s38, 0x30001
	s_and_b32 s39, s38, 1
	s_lshl_b32 s52, s100, 1
	s_add_u32 s52, s52, s36
	s_lshl_b32 s52, s52, 1
	s_add_u32 s52, s52, s39
	s_lshl_b32 s52, s52, 3
	s_add_u32 s52, s52, s41
	s_add_u32 s100, s101, 1
	s_cmp_eq_u32 s39, 0
	s_cselect_b32 s101, s101, s100
	s_cselect_b32 s92, 0, -1
	s_mov_b32 s98, 0xfffe0000
	s_cselect_b32 s98, 0x20000, s98
	s_mov_b32 s99, 0xffff0000
	s_cselect_b32 s99, 0x10000, s99
	s_mov_b32 s50, 0xfffc0000
	s_cselect_b32 s50, 0x40000, s50
	s_mov_b32 s51, 0xffffe000
	s_cselect_b32 s51, 0x2000, s51
	s_lshl_b32 s100, s101, 3
	s_add_u32 s100, s100, s41
	s_lshl_b32 s100, s100, 14
	s_lshl_b32 s53, s40, 10
	s_add_u32 s100, s100, s53
	s_add_u32 s100, s100, 0xc184000
	s_add_u32 s44, s96, s100
	s_addc_u32 s45, s97, 0
	s_lshl_b32 s100, s101, 1
	s_lshr_b32 s54, s41, 2
	s_add_u32 s100, s100, s54
	s_lshl_b32 s100, s100, 15
	s_add_u32 s100, s100, s53
	s_add_u32 s100, s100, 0xbe84000
	s_add_u32 s46, s96, s100
	s_addc_u32 s47, s97, 0
	s_lshl_b32 s100, s101, 1
	s_add_u32 s100, s100, s39
	s_lshl_b32 s100, s100, 3
	s_add_u32 s100, s100, s41
	s_lshl_b32 s54, s100, 14
	s_lshl_b32 s55, s42, 12
	s_add_u32 s54, s54, s55
	s_lshl_b32 s55, s43, 5
	s_add_u32 s54, s54, s55
	s_add_u32 s54, s54, 0xac84000
	s_add_u32 s48, s96, s54
	s_addc_u32 s49, s97, 0
	s_lshl_b32 s100, s100, 9
	s_add_u32 s54, s100, 0xcae4000
	s_add_u32 s58, s96, s54
	s_addc_u32 s59, s97, 0
	s_cmp_eq_u32 s39, 0
	s_cselect_b32 s54, 0x1fc, 0
	s_add_u32 s58, s58, s54
	s_addc_u32 s59, s59, 0
	global_load_dword v22, v2, s[58:59]
	s_add_u32 s58, s58, s51
	s_addc_u32 s59, s59, s92
	global_load_dword v23, v2, s[58:59]
	s_waitcnt lgkmcnt(0)
	s_barrier
	s_add_u32 s54, s100, 0xcb44000
	s_add_u32 s58, s96, s54
	s_addc_u32 s59, s97, 0
	s_cmp_eq_u32 s39, 0
	s_cbranch_scc1 .Lcs_fw
	s_sub_u32 s58, s58, 0x2000
	s_subb_u32 s59, s59, 0
.Lcs_fw:
	v_lshrrev_b32_e32 v18, 5, v16
	v_and_b32_e32 v19, 31, v16
	v_lshlrev_b32_e32 v18, 13, v18
	v_lshl_add_u32 v18, v19, 4, v18
	s_add_u32 s55, s53, 0x18000
	s_mov_b32 m0, s55
	s_nop 0
	global_load_lds_dwordx4 v18, s[58:59]
	s_and_b32 s54, s40, 3
	s_lshl_b32 s54, s54, 2
	v_add_u32_e32 v19, s54, v1
	v_and_b32_e32 v20, 15, v16
	v_xor_b32_e32 v19, v19, v20
	v_lshlrev_b32_e32 v19, 4, v19
	v_lshl_add_u32 v3, v1, 8, v19
	s_add_u32 m0, s53, 0x4000
	s_nop 0
	global_load_lds_dwordx4 v3, s[46:47]
	s_add_u32 s46, s46, 0x2000
	s_addc_u32 s47, s47, 0
	s_add_u32 m0, s53, 0x6000
	s_nop 0
	global_load_lds_dwordx4 v3, s[46:47]
	s_add_u32 s46, s46, 0x2000
	s_addc_u32 s47, s47, 0
	s_add_u32 m0, s53, 0x8000
	s_nop 0
	global_load_lds_dwordx4 v3, s[46:47]
	s_add_u32 s46, s46, 0x2000
	s_addc_u32 s47, s47, 0
	s_add_u32 m0, s53, 0xa000
	s_nop 0
	global_load_lds_dwordx4 v3, s[46:47]
	s_add_u32 m0, s53, 0x0
	s_nop 0
	global_load_lds_dwordx4 v3, s[44:45]
	s_add_u32 s44, s44, 0x2000
	s_addc_u32 s45, s45, 0
	s_add_u32 m0, s53, 0x2000
	s_nop 0
	global_load_lds_dwordx4 v3, s[44:45]
	s_sub_u32 s46, s46, 0x6000
	s_subb_u32 s47, s47, 0
	s_add_u32 s46, s46, s99
	s_addc_u32 s47, s47, s92
	s_sub_u32 s44, s44, 0x2000
	s_subb_u32 s45, s45, 0
	s_add_u32 s44, s44, s98
	s_addc_u32 s45, s45, s92
	s_add_u32 m0, s53, 0x10000
	s_nop 0
	global_load_lds_dwordx4 v3, s[46:47]
	s_add_u32 s46, s46, 0x2000
	s_addc_u32 s47, s47, 0
	s_add_u32 m0, s53, 0x12000
	s_nop 0
	global_load_lds_dwordx4 v3, s[46:47]
	s_add_u32 s46, s46, 0x2000
	s_addc_u32 s47, s47, 0
	s_add_u32 m0, s53, 0x14000
	s_nop 0
	global_load_lds_dwordx4 v3, s[46:47]
	s_add_u32 s46, s46, 0x2000
	s_addc_u32 s47, s47, 0
	s_add_u32 m0, s53, 0x16000
	s_nop 0
	global_load_lds_dwordx4 v3, s[46:47]
	s_add_u32 m0, s53, 0xc000
	s_nop 0
	global_load_lds_dwordx4 v3, s[44:45]
	s_add_u32 s44, s44, 0x2000
	s_addc_u32 s45, s45, 0
	s_add_u32 m0, s53, 0xe000
	s_nop 0
	global_load_lds_dwordx4 v3, s[44:45]
	v_lshlrev_b32_e32 v19, 8, v0
	s_lshl_b32 s54, s42, 12
	s_lshl_b32 s56, s43, 12
	s_add_u32 s56, s56, 0x4000
	v_add_u32_e32 v20, 0, v1
	v_xor_b32_e32 v20, v20, v0
	v_lshl_add_u32 v20, v20, 4, v19
	v_add_u32_e32 v4, s54, v20
	v_add_u32_e32 v8, s56, v20
	v_add_u32_e32 v20, 4, v1
	v_xor_b32_e32 v20, v20, v0
	v_lshl_add_u32 v20, v20, 4, v19
	v_add_u32_e32 v5, s54, v20
	v_add_u32_e32 v9, s56, v20
	v_add_u32_e32 v20, 8, v1
	v_xor_b32_e32 v20, v20, v0
	v_lshl_add_u32 v20, v20, 4, v19
	v_add_u32_e32 v6, s54, v20
	v_add_u32_e32 v10, s56, v20
	v_add_u32_e32 v20, 12, v1
	v_xor_b32_e32 v20, v20, v0
	v_lshl_add_u32 v20, v20, 4, v19
	v_add_u32_e32 v7, s54, v20
	v_add_u32_e32 v11, s56, v20
	v_lshlrev_b32_e32 v13, 9, v0
	v_lshl_add_u32 v13, v1, 4, v13
	v_lshrrev_b32_e32 v14, 1, v13
	v_lshl_add_u32 v12, v1, 5, s55
	v_mov_b32_e32 v88, 0
	v_mov_b32_e32 v89, 0
	v_mov_b32_e32 v90, 0
	v_mov_b32_e32 v91, 0
	v_mov_b32_e32 v92, 0
	v_mov_b32_e32 v93, 0
	v_mov_b32_e32 v94, 0
	v_mov_b32_e32 v95, 0
	v_mov_b32_e32 v96, 0
	v_mov_b32_e32 v97, 0
	v_mov_b32_e32 v98, 0
	v_mov_b32_e32 v99, 0
	v_mov_b32_e32 v100, 0
	v_mov_b32_e32 v101, 0
	v_mov_b32_e32 v102, 0
	v_mov_b32_e32 v103, 0
	s_waitcnt vmcnt(0)
	s_barrier
	s_xor_b32 s100, s39, 0
	s_lshl_b32 s100, s100, 9
	v_add_u32_e32 v21, s100, v12
	ds_read_b128 v[24:27], v4 offset:0
	ds_read_b128 v[32:35], v8 offset:0
	ds_read_b128 v[36:39], v8 offset:4096
	ds_read_b128 v[40:43], v8 offset:8192
	ds_read_b128 v[44:47], v8 offset:12288
	ds_read_b128 v[64:67], v21 offset:0
	ds_read_b128 v[68:71], v21 offset:16
	v_cvt_pk_bf16_f32 v16, v88, v89
	v_cvt_pk_bf16_f32 v17, v90, v91
	global_store_dwordx2 v14, v[16:17], s[48:49]
	s_nop 0
	v_cvt_pk_bf16_f32 v16, v92, v93
	v_cvt_pk_bf16_f32 v17, v94, v95
	global_store_dwordx2 v14, v[16:17], s[48:49] offset:32
	s_nop 0
	v_cvt_pk_bf16_f32 v16, v96, v97
	v_cvt_pk_bf16_f32 v17, v98, v99
	global_store_dwordx2 v14, v[16:17], s[48:49] offset:64
	s_nop 0
	v_cvt_pk_bf16_f32 v16, v100, v101
	v_cvt_pk_bf16_f32 v17, v102, v103
	global_store_dwordx2 v14, v[16:17], s[48:49] offset:96
	s_nop 0
	s_add_u32 s48, s48, s50
	s_addc_u32 s49, s49, s92
	v_mul_f32_e32 v15, 0x3fb8aa3b, v22
	v_exp_f32_e32 v15, v15
	s_nop 0
	v_mul_f32_e32 v88, v88, v15
	v_mul_f32_e32 v89, v89, v15
	v_mul_f32_e32 v90, v90, v15
	v_mul_f32_e32 v91, v91, v15
	v_mul_f32_e32 v92, v92, v15
	v_mul_f32_e32 v93, v93, v15
	v_mul_f32_e32 v94, v94, v15
	v_mul_f32_e32 v95, v95, v15
	v_mul_f32_e32 v96, v96, v15
	v_mul_f32_e32 v97, v97, v15
	v_mul_f32_e32 v98, v98, v15
	v_mul_f32_e32 v99, v99, v15
	v_mul_f32_e32 v100, v100, v15
	v_mul_f32_e32 v101, v101, v15
	v_mul_f32_e32 v102, v102, v15
	v_mul_f32_e32 v103, v103, v15
	ds_read_b128 v[28:31], v5 offset:0
	ds_read_b128 v[48:51], v9 offset:0
	ds_read_b128 v[52:55], v9 offset:4096
	ds_read_b128 v[56:59], v9 offset:8192
	ds_read_b128 v[60:63], v9 offset:12288
	ds_read_b128 v[72:75], v21 offset:128
	ds_read_b128 v[76:79], v21 offset:144
	s_waitcnt lgkmcnt(7)
	v_lshlrev_b32_e32 v18, 16, v24
	v_and_b32_e32 v19, s28, v24
	v_mul_f32_e32 v18, v18, v64
	v_mul_f32_e32 v19, v19, v65
	v_cvt_pk_bf16_f32 v80, v18, v19
	v_lshlrev_b32_e32 v18, 16, v25
	v_and_b32_e32 v19, s28, v25
	v_mul_f32_e32 v18, v18, v66
	v_mul_f32_e32 v19, v19, v67
	v_cvt_pk_bf16_f32 v81, v18, v19
	v_lshlrev_b32_e32 v18, 16, v26
	v_and_b32_e32 v19, s28, v26
	v_mul_f32_e32 v18, v18, v68
	v_mul_f32_e32 v19, v19, v69
	v_cvt_pk_bf16_f32 v82, v18, v19
	v_lshlrev_b32_e32 v18, 16, v27
	v_and_b32_e32 v19, s28, v27
	v_mul_f32_e32 v18, v18, v70
	v_mul_f32_e32 v19, v19, v71
	v_cvt_pk_bf16_f32 v83, v18, v19
	s_nop 1
	v_mfma_f32_16x16x32_bf16 v[88:91], v[32:35], v[80:83], v[88:91]
	v_mfma_f32_16x16x32_bf16 v[92:95], v[36:39], v[80:83], v[92:95]
	v_mfma_f32_16x16x32_bf16 v[96:99], v[40:43], v[80:83], v[96:99]
	v_mfma_f32_16x16x32_bf16 v[100:103], v[44:47], v[80:83], v[100:103]
	ds_read_b128 v[24:27], v6 offset:0
	ds_read_b128 v[32:35], v10 offset:0
	ds_read_b128 v[36:39], v10 offset:4096
	ds_read_b128 v[40:43], v10 offset:8192
	ds_read_b128 v[44:47], v10 offset:12288
	ds_read_b128 v[64:67], v21 offset:256
	ds_read_b128 v[68:71], v21 offset:272
	s_waitcnt lgkmcnt(7)
	v_lshlrev_b32_e32 v18, 16, v28
	v_and_b32_e32 v19, s28, v28
	v_mul_f32_e32 v18, v18, v72
	v_mul_f32_e32 v19, v19, v73
	v_cvt_pk_bf16_f32 v84, v18, v19
	v_lshlrev_b32_e32 v18, 16, v29
	v_and_b32_e32 v19, s28, v29
	v_mul_f32_e32 v18, v18, v74
	v_mul_f32_e32 v19, v19, v75
	v_cvt_pk_bf16_f32 v85, v18, v19
	v_lshlrev_b32_e32 v18, 16, v30
	v_and_b32_e32 v19, s28, v30
	v_mul_f32_e32 v18, v18, v76
	v_mul_f32_e32 v19, v19, v77
	v_cvt_pk_bf16_f32 v86, v18, v19
	v_lshlrev_b32_e32 v18, 16, v31
	v_and_b32_e32 v19, s28, v31
	v_mul_f32_e32 v18, v18, v78
	v_mul_f32_e32 v19, v19, v79
	v_cvt_pk_bf16_f32 v87, v18, v19
	s_nop 1
	v_mfma_f32_16x16x32_bf16 v[88:91], v[48:51], v[84:87], v[88:91]
	v_mfma_f32_16x16x32_bf16 v[92:95], v[52:55], v[84:87], v[92:95]
	v_mfma_f32_16x16x32_bf16 v[96:99], v[56:59], v[84:87], v[96:99]
	v_mfma_f32_16x16x32_bf16 v[100:103], v[60:63], v[84:87], v[100:103]
	ds_read_b128 v[28:31], v7 offset:0
	ds_read_b128 v[48:51], v11 offset:0
	ds_read_b128 v[52:55], v11 offset:4096
	ds_read_b128 v[56:59], v11 offset:8192
	ds_read_b128 v[60:63], v11 offset:12288
	ds_read_b128 v[72:75], v21 offset:384
	ds_read_b128 v[76:79], v21 offset:400
	s_waitcnt lgkmcnt(7)
	v_lshlrev_b32_e32 v18, 16, v24
	v_and_b32_e32 v19, s28, v24
	v_mul_f32_e32 v18, v18, v64
	v_mul_f32_e32 v19, v19, v65
	v_cvt_pk_bf16_f32 v80, v18, v19
	v_lshlrev_b32_e32 v18, 16, v25
	v_and_b32_e32 v19, s28, v25
	v_mul_f32_e32 v18, v18, v66
	v_mul_f32_e32 v19, v19, v67
	v_cvt_pk_bf16_f32 v81, v18, v19
	v_lshlrev_b32_e32 v18, 16, v26
	v_and_b32_e32 v19, s28, v26
	v_mul_f32_e32 v18, v18, v68
	v_mul_f32_e32 v19, v19, v69
	v_cvt_pk_bf16_f32 v82, v18, v19
	v_lshlrev_b32_e32 v18, 16, v27
	v_and_b32_e32 v19, s28, v27
	v_mul_f32_e32 v18, v18, v70
	v_mul_f32_e32 v19, v19, v71
	v_cvt_pk_bf16_f32 v83, v18, v19
	s_nop 1
	v_mfma_f32_16x16x32_bf16 v[88:91], v[32:35], v[80:83], v[88:91]
	v_mfma_f32_16x16x32_bf16 v[92:95], v[36:39], v[80:83], v[92:95]
	v_mfma_f32_16x16x32_bf16 v[96:99], v[40:43], v[80:83], v[96:99]
	v_mfma_f32_16x16x32_bf16 v[100:103], v[44:47], v[80:83], v[100:103]
	s_waitcnt lgkmcnt(0)
	v_lshlrev_b32_e32 v18, 16, v28
	v_and_b32_e32 v19, s28, v28
	v_mul_f32_e32 v18, v18, v72
	v_mul_f32_e32 v19, v19, v73
	v_cvt_pk_bf16_f32 v84, v18, v19
	v_lshlrev_b32_e32 v18, 16, v29
	v_and_b32_e32 v19, s28, v29
	v_mul_f32_e32 v18, v18, v74
	v_mul_f32_e32 v19, v19, v75
	v_cvt_pk_bf16_f32 v85, v18, v19
	v_lshlrev_b32_e32 v18, 16, v30
	v_and_b32_e32 v19, s28, v30
	v_mul_f32_e32 v18, v18, v76
	v_mul_f32_e32 v19, v19, v77
	v_cvt_pk_bf16_f32 v86, v18, v19
	v_lshlrev_b32_e32 v18, 16, v31
	v_and_b32_e32 v19, s28, v31
	v_mul_f32_e32 v18, v18, v78
	v_mul_f32_e32 v19, v19, v79
	v_cvt_pk_bf16_f32 v87, v18, v19
	s_nop 1
	v_mfma_f32_16x16x32_bf16 v[88:91], v[48:51], v[84:87], v[88:91]
	v_mfma_f32_16x16x32_bf16 v[92:95], v[52:55], v[84:87], v[92:95]
	v_mfma_f32_16x16x32_bf16 v[96:99], v[56:59], v[84:87], v[96:99]
	v_mfma_f32_16x16x32_bf16 v[100:103], v[60:63], v[84:87], v[100:103]
	s_nop 7
	s_xor_b32 s100, s39, 1
	s_lshl_b32 s100, s100, 9
	v_add_u32_e32 v21, s100, v12
	ds_read_b128 v[24:27], v4 offset:49152
	ds_read_b128 v[32:35], v8 offset:49152
	ds_read_b128 v[36:39], v8 offset:53248
	ds_read_b128 v[40:43], v8 offset:57344
	ds_read_b128 v[44:47], v8 offset:61440
	ds_read_b128 v[64:67], v21 offset:0
	ds_read_b128 v[68:71], v21 offset:16
	v_cvt_pk_bf16_f32 v16, v88, v89
	v_cvt_pk_bf16_f32 v17, v90, v91
	global_store_dwordx2 v14, v[16:17], s[48:49]
	s_nop 0
	v_cvt_pk_bf16_f32 v16, v92, v93
	v_cvt_pk_bf16_f32 v17, v94, v95
	global_store_dwordx2 v14, v[16:17], s[48:49] offset:32
	s_nop 0
	v_cvt_pk_bf16_f32 v16, v96, v97
	v_cvt_pk_bf16_f32 v17, v98, v99
	global_store_dwordx2 v14, v[16:17], s[48:49] offset:64
	s_nop 0
	v_cvt_pk_bf16_f32 v16, v100, v101
	v_cvt_pk_bf16_f32 v17, v102, v103
	global_store_dwordx2 v14, v[16:17], s[48:49] offset:96
	s_nop 0
	s_add_u32 s48, s48, s50
	s_addc_u32 s49, s49, s92
	v_mul_f32_e32 v15, 0x3fb8aa3b, v23
	v_exp_f32_e32 v15, v15
	s_nop 0
	v_mul_f32_e32 v88, v88, v15
	v_mul_f32_e32 v89, v89, v15
	v_mul_f32_e32 v90, v90, v15
	v_mul_f32_e32 v91, v91, v15
	v_mul_f32_e32 v92, v92, v15
	v_mul_f32_e32 v93, v93, v15
	v_mul_f32_e32 v94, v94, v15
	v_mul_f32_e32 v95, v95, v15
	v_mul_f32_e32 v96, v96, v15
	v_mul_f32_e32 v97, v97, v15
	v_mul_f32_e32 v98, v98, v15
	v_mul_f32_e32 v99, v99, v15
	v_mul_f32_e32 v100, v100, v15
	v_mul_f32_e32 v101, v101, v15
	v_mul_f32_e32 v102, v102, v15
	v_mul_f32_e32 v103, v103, v15
	ds_read_b128 v[28:31], v5 offset:49152
	ds_read_b128 v[48:51], v9 offset:49152
	ds_read_b128 v[52:55], v9 offset:53248
	ds_read_b128 v[56:59], v9 offset:57344
	ds_read_b128 v[60:63], v9 offset:61440
	ds_read_b128 v[72:75], v21 offset:128
	ds_read_b128 v[76:79], v21 offset:144
	s_waitcnt lgkmcnt(7)
	v_lshlrev_b32_e32 v18, 16, v24
	v_and_b32_e32 v19, s28, v24
	v_mul_f32_e32 v18, v18, v64
	v_mul_f32_e32 v19, v19, v65
	v_cvt_pk_bf16_f32 v80, v18, v19
	v_lshlrev_b32_e32 v18, 16, v25
	v_and_b32_e32 v19, s28, v25
	v_mul_f32_e32 v18, v18, v66
	v_mul_f32_e32 v19, v19, v67
	v_cvt_pk_bf16_f32 v81, v18, v19
	v_lshlrev_b32_e32 v18, 16, v26
	v_and_b32_e32 v19, s28, v26
	v_mul_f32_e32 v18, v18, v68
	v_mul_f32_e32 v19, v19, v69
	v_cvt_pk_bf16_f32 v82, v18, v19
	v_lshlrev_b32_e32 v18, 16, v27
	v_and_b32_e32 v19, s28, v27
	v_mul_f32_e32 v18, v18, v70
	v_mul_f32_e32 v19, v19, v71
	v_cvt_pk_bf16_f32 v83, v18, v19
	s_nop 1
	v_mfma_f32_16x16x32_bf16 v[88:91], v[32:35], v[80:83], v[88:91]
	v_mfma_f32_16x16x32_bf16 v[92:95], v[36:39], v[80:83], v[92:95]
	v_mfma_f32_16x16x32_bf16 v[96:99], v[40:43], v[80:83], v[96:99]
	v_mfma_f32_16x16x32_bf16 v[100:103], v[44:47], v[80:83], v[100:103]
	ds_read_b128 v[24:27], v6 offset:49152
	ds_read_b128 v[32:35], v10 offset:49152
	ds_read_b128 v[36:39], v10 offset:53248
	ds_read_b128 v[40:43], v10 offset:57344
	ds_read_b128 v[44:47], v10 offset:61440
	ds_read_b128 v[64:67], v21 offset:256
	ds_read_b128 v[68:71], v21 offset:272
	s_waitcnt lgkmcnt(7)
	v_lshlrev_b32_e32 v18, 16, v28
	v_and_b32_e32 v19, s28, v28
	v_mul_f32_e32 v18, v18, v72
	v_mul_f32_e32 v19, v19, v73
	v_cvt_pk_bf16_f32 v84, v18, v19
	v_lshlrev_b32_e32 v18, 16, v29
	v_and_b32_e32 v19, s28, v29
	v_mul_f32_e32 v18, v18, v74
	v_mul_f32_e32 v19, v19, v75
	v_cvt_pk_bf16_f32 v85, v18, v19
	v_lshlrev_b32_e32 v18, 16, v30
	v_and_b32_e32 v19, s28, v30
	v_mul_f32_e32 v18, v18, v76
	v_mul_f32_e32 v19, v19, v77
	v_cvt_pk_bf16_f32 v86, v18, v19
	v_lshlrev_b32_e32 v18, 16, v31
	v_and_b32_e32 v19, s28, v31
	v_mul_f32_e32 v18, v18, v78
	v_mul_f32_e32 v19, v19, v79
	v_cvt_pk_bf16_f32 v87, v18, v19
	s_nop 1
	v_mfma_f32_16x16x32_bf16 v[88:91], v[48:51], v[84:87], v[88:91]
	v_mfma_f32_16x16x32_bf16 v[92:95], v[52:55], v[84:87], v[92:95]
	v_mfma_f32_16x16x32_bf16 v[96:99], v[56:59], v[84:87], v[96:99]
	v_mfma_f32_16x16x32_bf16 v[100:103], v[60:63], v[84:87], v[100:103]
	ds_read_b128 v[28:31], v7 offset:49152
	ds_read_b128 v[48:51], v11 offset:49152
	ds_read_b128 v[52:55], v11 offset:53248
	ds_read_b128 v[56:59], v11 offset:57344
	ds_read_b128 v[60:63], v11 offset:61440
	ds_read_b128 v[72:75], v21 offset:384
	ds_read_b128 v[76:79], v21 offset:400
	s_waitcnt lgkmcnt(7)
	v_lshlrev_b32_e32 v18, 16, v24
	v_and_b32_e32 v19, s28, v24
	v_mul_f32_e32 v18, v18, v64
	v_mul_f32_e32 v19, v19, v65
	v_cvt_pk_bf16_f32 v80, v18, v19
	v_lshlrev_b32_e32 v18, 16, v25
	v_and_b32_e32 v19, s28, v25
	v_mul_f32_e32 v18, v18, v66
	v_mul_f32_e32 v19, v19, v67
	v_cvt_pk_bf16_f32 v81, v18, v19
	v_lshlrev_b32_e32 v18, 16, v26
	v_and_b32_e32 v19, s28, v26
	v_mul_f32_e32 v18, v18, v68
	v_mul_f32_e32 v19, v19, v69
	v_cvt_pk_bf16_f32 v82, v18, v19
	v_lshlrev_b32_e32 v18, 16, v27
	v_and_b32_e32 v19, s28, v27
	v_mul_f32_e32 v18, v18, v70
	v_mul_f32_e32 v19, v19, v71
	v_cvt_pk_bf16_f32 v83, v18, v19
	s_nop 1
	v_mfma_f32_16x16x32_bf16 v[88:91], v[32:35], v[80:83], v[88:91]
	v_mfma_f32_16x16x32_bf16 v[92:95], v[36:39], v[80:83], v[92:95]
	v_mfma_f32_16x16x32_bf16 v[96:99], v[40:43], v[80:83], v[96:99]
	v_mfma_f32_16x16x32_bf16 v[100:103], v[44:47], v[80:83], v[100:103]
	s_waitcnt lgkmcnt(0)
	v_lshlrev_b32_e32 v18, 16, v28
	v_and_b32_e32 v19, s28, v28
	v_mul_f32_e32 v18, v18, v72
	v_mul_f32_e32 v19, v19, v73
	v_cvt_pk_bf16_f32 v84, v18, v19
	v_lshlrev_b32_e32 v18, 16, v29
	v_and_b32_e32 v19, s28, v29
	v_mul_f32_e32 v18, v18, v74
	v_mul_f32_e32 v19, v19, v75
	v_cvt_pk_bf16_f32 v85, v18, v19
	v_lshlrev_b32_e32 v18, 16, v30
	v_and_b32_e32 v19, s28, v30
	v_mul_f32_e32 v18, v18, v76
	v_mul_f32_e32 v19, v19, v77
	v_cvt_pk_bf16_f32 v86, v18, v19
	v_lshlrev_b32_e32 v18, 16, v31
	v_and_b32_e32 v19, s28, v31
	v_mul_f32_e32 v18, v18, v78
	v_mul_f32_e32 v19, v19, v79
	v_cvt_pk_bf16_f32 v87, v18, v19
	s_nop 1
	v_mfma_f32_16x16x32_bf16 v[88:91], v[48:51], v[84:87], v[88:91]
	v_mfma_f32_16x16x32_bf16 v[92:95], v[52:55], v[84:87], v[92:95]
	v_mfma_f32_16x16x32_bf16 v[96:99], v[56:59], v[84:87], v[96:99]
	v_mfma_f32_16x16x32_bf16 v[100:103], v[60:63], v[84:87], v[100:103]
	s_nop 7
	s_barrier
	v_readlane_b32 s58, v237, 7
	v_readlane_b32 s59, v237, 8
	s_lshl_b32 s100, s52, 15
	s_lshl_b32 s54, s42, 13
	s_add_u32 s100, s100, s54
	s_lshl_b32 s54, s43, 6
	s_add_u32 s100, s100, s54
	s_add_u32 s100, s100, 0x1800000
	s_add_u32 s58, s58, s100
	s_addc_u32 s59, s59, 0
	s_nop 3
	global_store_dwordx4 v13, v[88:91], s[58:59]
	global_store_dwordx4 v13, v[92:95], s[58:59] offset:64
	global_store_dwordx4 v13, v[96:99], s[58:59] offset:128
	global_store_dwordx4 v13, v[100:103], s[58:59] offset:192
	s_branch .Lsp3_e0

.Lsp3_cctx:
.Lsp3_done:
	s_waitcnt vmcnt(0) lgkmcnt(0)
	s_branch .LBB0_854
